# P9 gate-up K-loop: post-MMA barrier moved above the last 2 MFMAs of each MMA block (other wave group's MFMAs queue behind them)
# baseline (speedup 1.0000x reference)
; #define PG8_STAGE(srd, bufoff, goff, voff) do { _Pragma("unroll") for (int _i = 0; _i < 2; ++_i) \
;         __builtin_amdgcn_raw_ptr_buffer_load_lds(srd, (PG8_LAS unsigned*)(lds + (bufoff) + ldsw + _i * 8192), 16, (voff)[_i], (goff), 0, 0); } while (0)
; #define PG8_LDA(dst, b, h) do { _Pragma("unroll") for (int m = 0; m < 4; ++m) _Pragma("unroll") for (int k = 0; k < 2; ++k) dst[m][k] = *(const PG8_LAS bf16x8*)(lds + PG8_SA(b, h) + aoff + m * 2048 + k * 1024); } while (0)
; #define PG8_LDB(dst, b, h) do { _Pragma("unroll") for (int n = 0; n < 2; ++n) _Pragma("unroll") for (int k = 0; k < 2; ++k) dst[n][k] = *(const PG8_LAS bf16x8*)(lds + PG8_SB(b, h) + boff + n * 2048 + k * 1024); } while (0)
; #define PG8_MMA(ai, bj, At, Bt) do { __builtin_amdgcn_s_setprio(1); _Pragma("unroll") for (int m = 0; m < 4; ++m) _Pragma("unroll") for (int n = 0; n < 2; ++n) _Pragma("unroll") for (int k = 0; k < 2; ++k) \
;         acc[ai][bj][m][n] = __builtin_amdgcn_mfma_f32_16x16x32_bf16(Bt[n][k], At[m][k], acc[ai][bj][m][n], 0, 0, 0); __builtin_amdgcn_s_setprio(0); } while (0)
; #define PG8_BAR __builtin_amdgcn_s_barrier()
; template <class Epi, class Sched, bool ALIGN_EPI = true>
; __device__ __forceinline__ void gemm_phase(PG8_LAS unsigned char* lds, const Gemm g, const Sched& S, const Epi& E) {
;     ...
;             PG8_LDB(B0, 0, 0); PG8_LDB(B1, 0, 1); PG8_SCHED; PG8_LDA(At, 0, 0); PG8_STAGE(srdA, PG8_SA(1, 1), a1 + hstepA, voffA);
;             PG8_WAIT_V(8); PG8_WAIT_L(0); PG8_BAR; PG8_MMA(0, 0, At, B0); PG8_MMA(0, 1, At, B1); PG8_BAR; PG8_SCHED;
;             PG8_LDA(At, 0, 1); PG8_STAGE(srdB, PG8_SB(0, 0), b2, voffB); PG8_STAGE(srdB, PG8_SB(0, 1), b2 + hstepB, voffB); PG8_STAGE(srdA, PG8_SA(0, 0), a2, voffA);
;             PG8_WAIT_V(8); PG8_WAIT_L(0); PG8_BAR; PG8_MMA(1, 0, At, B0); PG8_MMA(1, 1, At, B1); PG8_BAR; PG8_SCHED;
;             PG8_LDB(B0, 1, 0); PG8_LDB(B1, 1, 1); PG8_SCHED; PG8_LDA(At, 1, 0); PG8_STAGE(srdA, PG8_SA(0, 1), a2 + hstepA, voffA);
;             PG8_WAIT_V(8); PG8_WAIT_L(0); PG8_BAR; PG8_MMA(0, 0, At, B0); PG8_MMA(0, 1, At, B1); PG8_BAR; PG8_SCHED;
;             PG8_LDA(At, 1, 1); PG8_STAGE(srdB, PG8_SB(1, 0), b3, voffB); PG8_STAGE(srdB, PG8_SB(1, 1), b3 + hstepB, voffB); PG8_STAGE(srdA, PG8_SA(1, 0), a3, voffA);
;             PG8_WAIT_V(8); PG8_WAIT_L(0); PG8_BAR; PG8_MMA(1, 0, At, B0); PG8_MMA(1, 1, At, B1); PG8_BAR; PG8_SCHED;
.LBB0_896:
	ds_read_b128 v[154:157], v147
	ds_read_b128 v[172:175], v147 offset:1024
	ds_read_b128 v[176:179], v147 offset:2048
	ds_read_b128 v[180:183], v147 offset:3072
	ds_read_b128 v[184:187], v148
	ds_read_b128 v[188:191], v148 offset:1024
	ds_read_b128 v[192:195], v148 offset:2048
	ds_read_b128 v[196:199], v148 offset:3072
	s_add_i32 s26, s53, 0xfff80080
	s_cmp_eq_u32 s55, 28
	s_cselect_b32 s58, s51, s26
	s_cselect_b32 s57, s52, s54
	s_or_b32 s56, s58, 0x80
	s_mov_b32 m0, s44
	ds_read_b128 v[200:203], v149
	ds_read_b128 v[204:207], v149 offset:1024
	ds_read_b128 v[208:211], v149 offset:2048
	ds_read_b128 v[212:215], v149 offset:3072
	ds_read_b128 v[216:219], v149 offset:4096
	ds_read_b128 v[220:223], v149 offset:5120
	ds_read_b128 v[224:227], v149 offset:6144
	ds_read_b128 v[228:231], v149 offset:7168
	buffer_load_dwordx4 v135, s[16:19], s53 offen lds
	s_mov_b32 m0, s45
	s_nop 0
	buffer_load_dwordx4 v137, s[16:19], s53 offen lds
	s_waitcnt vmcnt(8)
	s_waitcnt lgkmcnt(0)
	s_barrier
	s_setprio 1
	s_waitcnt lgkmcnt(7)
	v_mfma_f32_16x16x32_bf16 v[116:119], v[154:157], v[200:203], v[116:119]
	v_mfma_f32_16x16x32_bf16 v[112:115], v[176:179], v[200:203], v[112:115]
	s_waitcnt lgkmcnt(5)
	v_mfma_f32_16x16x32_bf16 v[100:103], v[154:157], v[208:211], v[100:103]
	v_mfma_f32_16x16x32_bf16 v[96:99], v[176:179], v[208:211], v[96:99]
	s_waitcnt lgkmcnt(3)
	v_mfma_f32_16x16x32_bf16 v[84:87], v[154:157], v[216:219], v[84:87]
	v_mfma_f32_16x16x32_bf16 v[80:83], v[176:179], v[216:219], v[80:83]
	s_waitcnt lgkmcnt(1)
	v_mfma_f32_16x16x32_bf16 v[68:71], v[154:157], v[224:227], v[68:71]
	v_mfma_f32_16x16x32_bf16 v[64:67], v[176:179], v[224:227], v[64:67]
	v_mfma_f32_16x16x32_bf16 v[116:119], v[172:175], v[204:207], v[116:119]
	v_mfma_f32_16x16x32_bf16 v[112:115], v[180:183], v[204:207], v[112:115]
	v_mfma_f32_16x16x32_bf16 v[100:103], v[172:175], v[212:215], v[100:103]
	v_mfma_f32_16x16x32_bf16 v[96:99], v[180:183], v[212:215], v[96:99]
	v_mfma_f32_16x16x32_bf16 v[84:87], v[172:175], v[220:223], v[84:87]
	v_mfma_f32_16x16x32_bf16 v[80:83], v[180:183], v[220:223], v[80:83]
	s_waitcnt lgkmcnt(0)
	v_mfma_f32_16x16x32_bf16 v[68:71], v[172:175], v[228:231], v[68:71]
	v_mfma_f32_16x16x32_bf16 v[64:67], v[180:183], v[228:231], v[64:67]
	s_setprio 0
	s_setprio 1
	v_mfma_f32_16x16x32_bf16 v[124:127], v[184:187], v[200:203], v[124:127]
	v_mfma_f32_16x16x32_bf16 v[120:123], v[192:195], v[200:203], v[120:123]
	v_mfma_f32_16x16x32_bf16 v[108:111], v[184:187], v[208:211], v[108:111]
	v_mfma_f32_16x16x32_bf16 v[104:107], v[192:195], v[208:211], v[104:107]
	v_mfma_f32_16x16x32_bf16 v[92:95], v[184:187], v[216:219], v[92:95]
	v_mfma_f32_16x16x32_bf16 v[88:91], v[192:195], v[216:219], v[88:91]
	v_mfma_f32_16x16x32_bf16 v[76:79], v[184:187], v[224:227], v[76:79]
	v_mfma_f32_16x16x32_bf16 v[72:75], v[192:195], v[224:227], v[72:75]
	v_mfma_f32_16x16x32_bf16 v[124:127], v[188:191], v[204:207], v[124:127]
	v_mfma_f32_16x16x32_bf16 v[120:123], v[196:199], v[204:207], v[120:123]
	v_mfma_f32_16x16x32_bf16 v[108:111], v[188:191], v[212:215], v[108:111]
	v_mfma_f32_16x16x32_bf16 v[104:107], v[196:199], v[212:215], v[104:107]
	v_mfma_f32_16x16x32_bf16 v[92:95], v[188:191], v[220:223], v[92:95]
	v_mfma_f32_16x16x32_bf16 v[88:91], v[196:199], v[220:223], v[88:91]
	s_barrier
	v_mfma_f32_16x16x32_bf16 v[76:79], v[188:191], v[228:231], v[76:79]
	v_mfma_f32_16x16x32_bf16 v[72:75], v[196:199], v[228:231], v[72:75]
	s_setprio 0
	s_mov_b32 m0, s28
	s_mov_b32 s26, s18
	s_mov_b32 s27, s19
	ds_read_b128 v[200:203], v149 offset:16384
	ds_read_b128 v[204:207], v149 offset:17408
	ds_read_b128 v[208:211], v149 offset:18432
	ds_read_b128 v[212:215], v149 offset:19456
	ds_read_b128 v[216:219], v149 offset:20480
	ds_read_b128 v[220:223], v149 offset:21504
	ds_read_b128 v[224:227], v149 offset:22528
	ds_read_b128 v[228:231], v149 offset:23552
	buffer_load_dwordx4 v136, s[24:27], s57 offen lds
	s_mov_b32 m0, s29
	s_add_i32 s59, s57, 0x80000
	buffer_load_dwordx4 v138, s[24:27], s57 offen lds
	s_mov_b32 m0, s30
	s_nop 0
	buffer_load_dwordx4 v136, s[24:27], s59 offen lds
	s_mov_b32 m0, s31
	s_nop 0
	buffer_load_dwordx4 v138, s[24:27], s59 offen lds
	s_mov_b32 m0, s21
	s_nop 0
	buffer_load_dwordx4 v135, s[16:19], s58 offen lds
	s_mov_b32 m0, s34
	s_nop 0
	buffer_load_dwordx4 v137, s[16:19], s58 offen lds
	s_waitcnt vmcnt(8)
	s_waitcnt lgkmcnt(0)
	s_barrier
	s_setprio 1
	s_waitcnt lgkmcnt(7)
	v_mfma_f32_16x16x32_bf16 v[52:55], v[154:157], v[200:203], v[52:55]
	v_mfma_f32_16x16x32_bf16 v[48:51], v[176:179], v[200:203], v[48:51]
	s_waitcnt lgkmcnt(5)
	v_mfma_f32_16x16x32_bf16 v[36:39], v[154:157], v[208:211], v[36:39]
	v_mfma_f32_16x16x32_bf16 v[32:35], v[176:179], v[208:211], v[32:35]
	s_waitcnt lgkmcnt(3)
	v_mfma_f32_16x16x32_bf16 v[20:23], v[154:157], v[216:219], v[20:23]
	v_mfma_f32_16x16x32_bf16 v[16:19], v[176:179], v[216:219], v[16:19]
	s_waitcnt lgkmcnt(1)
	v_mfma_f32_16x16x32_bf16 v[8:11], v[154:157], v[224:227], v[8:11]
	v_mfma_f32_16x16x32_bf16 v[4:7], v[176:179], v[224:227], v[4:7]
	v_mfma_f32_16x16x32_bf16 v[52:55], v[172:175], v[204:207], v[52:55]
	v_mfma_f32_16x16x32_bf16 v[48:51], v[180:183], v[204:207], v[48:51]
	v_mfma_f32_16x16x32_bf16 v[36:39], v[172:175], v[212:215], v[36:39]
	v_mfma_f32_16x16x32_bf16 v[32:35], v[180:183], v[212:215], v[32:35]
	v_mfma_f32_16x16x32_bf16 v[20:23], v[172:175], v[220:223], v[20:23]
	v_mfma_f32_16x16x32_bf16 v[16:19], v[180:183], v[220:223], v[16:19]
	s_waitcnt lgkmcnt(0)
	v_mfma_f32_16x16x32_bf16 v[8:11], v[172:175], v[228:231], v[8:11]
	v_mfma_f32_16x16x32_bf16 v[4:7], v[180:183], v[228:231], v[4:7]
	s_setprio 0
	s_setprio 1
	v_mfma_f32_16x16x32_bf16 v[60:63], v[184:187], v[200:203], v[60:63]
	v_mfma_f32_16x16x32_bf16 v[56:59], v[192:195], v[200:203], v[56:59]
	v_mfma_f32_16x16x32_bf16 v[44:47], v[184:187], v[208:211], v[44:47]
	v_mfma_f32_16x16x32_bf16 v[40:43], v[192:195], v[208:211], v[40:43]
	v_mfma_f32_16x16x32_bf16 v[28:31], v[184:187], v[216:219], v[28:31]
	v_mfma_f32_16x16x32_bf16 v[24:27], v[192:195], v[216:219], v[24:27]
	v_mfma_f32_16x16x32_bf16 v[12:15], v[184:187], v[224:227], v[12:15]
	v_mfma_f32_16x16x32_bf16 v[0:3], v[192:195], v[224:227], v[0:3]
	v_mfma_f32_16x16x32_bf16 v[60:63], v[188:191], v[204:207], v[60:63]
	v_mfma_f32_16x16x32_bf16 v[56:59], v[196:199], v[204:207], v[56:59]
	v_mfma_f32_16x16x32_bf16 v[44:47], v[188:191], v[212:215], v[44:47]
	v_mfma_f32_16x16x32_bf16 v[40:43], v[196:199], v[212:215], v[40:43]
	v_mfma_f32_16x16x32_bf16 v[28:31], v[188:191], v[220:223], v[28:31]
	v_mfma_f32_16x16x32_bf16 v[24:27], v[196:199], v[220:223], v[24:27]
	s_barrier
; #define PG8_STAGE(srd, bufoff, goff, voff) do { _Pragma("unroll") for (int _i = 0; _i < 2; ++_i) \
;         __builtin_amdgcn_raw_ptr_buffer_load_lds(srd, (PG8_LAS unsigned*)(lds + (bufoff) + ldsw + _i * 8192), 16, (voff)[_i], (goff), 0, 0); } while (0)
; #define PG8_LDA(dst, b, h) do { _Pragma("unroll") for (int m = 0; m < 4; ++m) _Pragma("unroll") for (int k = 0; k < 2; ++k) dst[m][k] = *(const PG8_LAS bf16x8*)(lds + PG8_SA(b, h) + aoff + m * 2048 + k * 1024); } while (0)
; #define PG8_LDB(dst, b, h) do { _Pragma("unroll") for (int n = 0; n < 2; ++n) _Pragma("unroll") for (int k = 0; k < 2; ++k) dst[n][k] = *(const PG8_LAS bf16x8*)(lds + PG8_SB(b, h) + boff + n * 2048 + k * 1024); } while (0)
; #define PG8_MMA(ai, bj, At, Bt) do { __builtin_amdgcn_s_setprio(1); _Pragma("unroll") for (int m = 0; m < 4; ++m) _Pragma("unroll") for (int n = 0; n < 2; ++n) _Pragma("unroll") for (int k = 0; k < 2; ++k) \
;         acc[ai][bj][m][n] = __builtin_amdgcn_mfma_f32_16x16x32_bf16(Bt[n][k], At[m][k], acc[ai][bj][m][n], 0, 0, 0); __builtin_amdgcn_s_setprio(0); } while (0)
; #define PG8_BAR __builtin_amdgcn_s_barrier()
; template <class Epi, class Sched, bool ALIGN_EPI = true>
; __device__ __forceinline__ void gemm_phase(PG8_LAS unsigned char* lds, const Gemm g, const Sched& S, const Epi& E) {
;     ...
;             PG8_LDB(B0, 0, 0); PG8_LDB(B1, 0, 1); PG8_SCHED; PG8_LDA(At, 0, 0); PG8_STAGE(srdA, PG8_SA(1, 1), a1 + hstepA, voffA);
;             PG8_WAIT_V(8); PG8_WAIT_L(0); PG8_BAR; PG8_MMA(0, 0, At, B0); PG8_MMA(0, 1, At, B1); PG8_BAR; PG8_SCHED;
;             PG8_LDA(At, 0, 1); PG8_STAGE(srdB, PG8_SB(0, 0), b2, voffB); PG8_STAGE(srdB, PG8_SB(0, 1), b2 + hstepB, voffB); PG8_STAGE(srdA, PG8_SA(0, 0), a2, voffA);
;             PG8_WAIT_V(8); PG8_WAIT_L(0); PG8_BAR; PG8_MMA(1, 0, At, B0); PG8_MMA(1, 1, At, B1); PG8_BAR; PG8_SCHED;
;             PG8_LDB(B0, 1, 0); PG8_LDB(B1, 1, 1); PG8_SCHED; PG8_LDA(At, 1, 0); PG8_STAGE(srdA, PG8_SA(0, 1), a2 + hstepA, voffA);
;             PG8_WAIT_V(8); PG8_WAIT_L(0); PG8_BAR; PG8_MMA(0, 0, At, B0); PG8_MMA(0, 1, At, B1); PG8_BAR; PG8_SCHED;
;             PG8_LDA(At, 1, 1); PG8_STAGE(srdB, PG8_SB(1, 0), b3, voffB); PG8_STAGE(srdB, PG8_SB(1, 1), b3 + hstepB, voffB); PG8_STAGE(srdA, PG8_SA(1, 0), a3, voffA);
;             PG8_WAIT_V(8); PG8_WAIT_L(0); PG8_BAR; PG8_MMA(1, 0, At, B0); PG8_MMA(1, 1, At, B1); PG8_BAR; PG8_SCHED;
	v_mfma_f32_16x16x32_bf16 v[12:15], v[188:191], v[228:231], v[12:15]
	v_mfma_f32_16x16x32_bf16 v[0:3], v[196:199], v[228:231], v[0:3]
	s_setprio 0
	ds_read_b128 v[154:157], v150
	ds_read_b128 v[172:175], v150 offset:1024
	ds_read_b128 v[176:179], v150 offset:2048
	ds_read_b128 v[180:183], v150 offset:3072
	ds_read_b128 v[184:187], v151
	ds_read_b128 v[188:191], v151 offset:1024
	ds_read_b128 v[192:195], v151 offset:2048
	ds_read_b128 v[196:199], v151 offset:3072
	s_add_i32 s58, s58, 0x80000
	s_mov_b32 m0, s35
	ds_read_b128 v[200:203], v149 offset:32768
	ds_read_b128 v[204:207], v149 offset:33792
	ds_read_b128 v[208:211], v149 offset:34816
	ds_read_b128 v[212:215], v149 offset:35840
	ds_read_b128 v[216:219], v149 offset:36864
	ds_read_b128 v[220:223], v149 offset:37888
	ds_read_b128 v[224:227], v149 offset:38912
	ds_read_b128 v[228:231], v149 offset:39936
	buffer_load_dwordx4 v135, s[16:19], s58 offen lds
	s_mov_b32 m0, s36
	s_nop 0
	buffer_load_dwordx4 v137, s[16:19], s58 offen lds
	s_waitcnt vmcnt(8)
	s_waitcnt lgkmcnt(0)
	s_barrier
	s_setprio 1
	s_waitcnt lgkmcnt(7)
	v_mfma_f32_16x16x32_bf16 v[116:119], v[154:157], v[200:203], v[116:119]
	v_mfma_f32_16x16x32_bf16 v[112:115], v[176:179], v[200:203], v[112:115]
	s_waitcnt lgkmcnt(5)
	v_mfma_f32_16x16x32_bf16 v[100:103], v[154:157], v[208:211], v[100:103]
	v_mfma_f32_16x16x32_bf16 v[96:99], v[176:179], v[208:211], v[96:99]
	s_waitcnt lgkmcnt(3)
	v_mfma_f32_16x16x32_bf16 v[84:87], v[154:157], v[216:219], v[84:87]
	v_mfma_f32_16x16x32_bf16 v[80:83], v[176:179], v[216:219], v[80:83]
	s_waitcnt lgkmcnt(1)
	v_mfma_f32_16x16x32_bf16 v[68:71], v[154:157], v[224:227], v[68:71]
	v_mfma_f32_16x16x32_bf16 v[64:67], v[176:179], v[224:227], v[64:67]
	v_mfma_f32_16x16x32_bf16 v[116:119], v[172:175], v[204:207], v[116:119]
	v_mfma_f32_16x16x32_bf16 v[112:115], v[180:183], v[204:207], v[112:115]
	v_mfma_f32_16x16x32_bf16 v[100:103], v[172:175], v[212:215], v[100:103]
	v_mfma_f32_16x16x32_bf16 v[96:99], v[180:183], v[212:215], v[96:99]
	v_mfma_f32_16x16x32_bf16 v[84:87], v[172:175], v[220:223], v[84:87]
	v_mfma_f32_16x16x32_bf16 v[80:83], v[180:183], v[220:223], v[80:83]
	s_waitcnt lgkmcnt(0)
	v_mfma_f32_16x16x32_bf16 v[68:71], v[172:175], v[228:231], v[68:71]
	v_mfma_f32_16x16x32_bf16 v[64:67], v[180:183], v[228:231], v[64:67]
	s_setprio 0
	s_setprio 1
	v_mfma_f32_16x16x32_bf16 v[124:127], v[184:187], v[200:203], v[124:127]
	v_mfma_f32_16x16x32_bf16 v[120:123], v[192:195], v[200:203], v[120:123]
	v_mfma_f32_16x16x32_bf16 v[108:111], v[184:187], v[208:211], v[108:111]
	v_mfma_f32_16x16x32_bf16 v[104:107], v[192:195], v[208:211], v[104:107]
	v_mfma_f32_16x16x32_bf16 v[92:95], v[184:187], v[216:219], v[92:95]
	v_mfma_f32_16x16x32_bf16 v[88:91], v[192:195], v[216:219], v[88:91]
	v_mfma_f32_16x16x32_bf16 v[76:79], v[184:187], v[224:227], v[76:79]
	v_mfma_f32_16x16x32_bf16 v[72:75], v[192:195], v[224:227], v[72:75]
	v_mfma_f32_16x16x32_bf16 v[124:127], v[188:191], v[204:207], v[124:127]
	v_mfma_f32_16x16x32_bf16 v[120:123], v[196:199], v[204:207], v[120:123]
	v_mfma_f32_16x16x32_bf16 v[108:111], v[188:191], v[212:215], v[108:111]
	v_mfma_f32_16x16x32_bf16 v[104:107], v[196:199], v[212:215], v[104:107]
	v_mfma_f32_16x16x32_bf16 v[92:95], v[188:191], v[220:223], v[92:95]
	v_mfma_f32_16x16x32_bf16 v[88:91], v[196:199], v[220:223], v[88:91]
	s_barrier
	v_mfma_f32_16x16x32_bf16 v[76:79], v[188:191], v[228:231], v[76:79]
	v_mfma_f32_16x16x32_bf16 v[72:75], v[196:199], v[228:231], v[72:75]
	s_setprio 0
	s_mov_b32 m0, s38
	s_or_b32 s58, s57, 0x80
	ds_read_b128 v[200:203], v149 offset:49152
	ds_read_b128 v[204:207], v149 offset:50176
	ds_read_b128 v[208:211], v149 offset:51200
	ds_read_b128 v[212:215], v149 offset:52224
	ds_read_b128 v[216:219], v149 offset:53248
	ds_read_b128 v[220:223], v149 offset:54272
	ds_read_b128 v[224:227], v149 offset:55296
	ds_read_b128 v[228:231], v149 offset:56320
	buffer_load_dwordx4 v136, s[24:27], s58 offen lds
	s_mov_b32 m0, s39
	s_add_i32 s57, s57, 0x80080
	buffer_load_dwordx4 v138, s[24:27], s58 offen lds
	s_mov_b32 m0, s42
	s_nop 0
	buffer_load_dwordx4 v136, s[24:27], s57 offen lds
	s_mov_b32 m0, s43
	s_nop 0
	buffer_load_dwordx4 v138, s[24:27], s57 offen lds
	s_mov_b32 m0, s40
	s_nop 0
	buffer_load_dwordx4 v135, s[16:19], s56 offen lds
	s_mov_b32 m0, s41
	s_nop 0
	buffer_load_dwordx4 v137, s[16:19], s56 offen lds
	s_waitcnt vmcnt(8)
	s_waitcnt lgkmcnt(0)
	s_barrier
	s_setprio 1
	s_waitcnt lgkmcnt(7)
	v_mfma_f32_16x16x32_bf16 v[52:55], v[154:157], v[200:203], v[52:55]
	v_mfma_f32_16x16x32_bf16 v[48:51], v[176:179], v[200:203], v[48:51]
	s_waitcnt lgkmcnt(5)
	v_mfma_f32_16x16x32_bf16 v[36:39], v[154:157], v[208:211], v[36:39]
	v_mfma_f32_16x16x32_bf16 v[32:35], v[176:179], v[208:211], v[32:35]
	s_waitcnt lgkmcnt(3)
	v_mfma_f32_16x16x32_bf16 v[20:23], v[154:157], v[216:219], v[20:23]
	v_mfma_f32_16x16x32_bf16 v[16:19], v[176:179], v[216:219], v[16:19]
	s_waitcnt lgkmcnt(1)
	v_mfma_f32_16x16x32_bf16 v[8:11], v[154:157], v[224:227], v[8:11]
	v_mfma_f32_16x16x32_bf16 v[4:7], v[176:179], v[224:227], v[4:7]
	v_mfma_f32_16x16x32_bf16 v[52:55], v[172:175], v[204:207], v[52:55]
	v_mfma_f32_16x16x32_bf16 v[48:51], v[180:183], v[204:207], v[48:51]
	v_mfma_f32_16x16x32_bf16 v[36:39], v[172:175], v[212:215], v[36:39]
	v_mfma_f32_16x16x32_bf16 v[32:35], v[180:183], v[212:215], v[32:35]
	v_mfma_f32_16x16x32_bf16 v[20:23], v[172:175], v[220:223], v[20:23]
	v_mfma_f32_16x16x32_bf16 v[16:19], v[180:183], v[220:223], v[16:19]
	s_waitcnt lgkmcnt(0)
	v_mfma_f32_16x16x32_bf16 v[8:11], v[172:175], v[228:231], v[8:11]
	v_mfma_f32_16x16x32_bf16 v[4:7], v[180:183], v[228:231], v[4:7]
	s_setprio 0
	s_setprio 1
	v_mfma_f32_16x16x32_bf16 v[60:63], v[184:187], v[200:203], v[60:63]
	v_mfma_f32_16x16x32_bf16 v[56:59], v[192:195], v[200:203], v[56:59]
	v_mfma_f32_16x16x32_bf16 v[44:47], v[184:187], v[208:211], v[44:47]
	v_mfma_f32_16x16x32_bf16 v[40:43], v[192:195], v[208:211], v[40:43]
	v_mfma_f32_16x16x32_bf16 v[28:31], v[184:187], v[216:219], v[28:31]
	v_mfma_f32_16x16x32_bf16 v[24:27], v[192:195], v[216:219], v[24:27]
	v_mfma_f32_16x16x32_bf16 v[12:15], v[184:187], v[224:227], v[12:15]
	v_mfma_f32_16x16x32_bf16 v[0:3], v[192:195], v[224:227], v[0:3]
	v_mfma_f32_16x16x32_bf16 v[60:63], v[188:191], v[204:207], v[60:63]
	v_mfma_f32_16x16x32_bf16 v[56:59], v[196:199], v[204:207], v[56:59]
	v_mfma_f32_16x16x32_bf16 v[44:47], v[188:191], v[212:215], v[44:47]
	v_mfma_f32_16x16x32_bf16 v[40:43], v[196:199], v[212:215], v[40:43]
	v_mfma_f32_16x16x32_bf16 v[28:31], v[188:191], v[220:223], v[28:31]
	v_mfma_f32_16x16x32_bf16 v[24:27], v[196:199], v[220:223], v[24:27]
	s_barrier
	v_mfma_f32_16x16x32_bf16 v[12:15], v[188:191], v[228:231], v[12:15]
	v_mfma_f32_16x16x32_bf16 v[0:3], v[196:199], v[228:231], v[0:3]
	s_setprio 0
	s_add_i32 s55, s55, 2
	s_addk_i32 s53, 0x100
	s_addk_i32 s54, 0x100
	s_cmp_gt_u32 s55, 29
	s_cbranch_scc0 .LBB0_896
	s_and_b64 vcc, exec, s[10:11]
	s_cbranch_vccz .LBB0_899
	s_barrier
